# gdn_pre phase: static s_setprio 1 for waves 4-7 (on top of the attention static priority)
# baseline (speedup 1.0000x reference)
; __device__ __forceinline__ int bidx() { int b = blockIdx.x; OPAQUE_S(b); return b; }
; __device__ __forceinline__ float bf2f(bf16_t b) { return __uint_as_float(((unsigned)b) << 16); }
; __device__ __forceinline__ void gdn_pre_phase(const Args& a, LAS unsigned char* lds, int slot) {
;     ...
;     for (size_t i = (size_t)bidx() * NTHREADS + tid0; i < 48ull * 3 * 3072; i += (size_t)gridDim.x * NTHREADS) {
;         const int s = (int)(i / (3 * 3072)), j = (int)((i / 3072) % 3), c = (int)(i % 3072);
;         if (s < 32) a.out[O_GCP + ((size_t)(slot * 32 + s) * 3 + j) * 3072 + c] = bf2f(QKV[((size_t)s * 2048 + 2045 + j) * 3072 + c]);
;         else a.out[O_GCS + ((size_t)(slot * 16 + s - 32) * 3 + j) * 3072 + c] = bf2f(QKV[((size_t)NTP + (s - 32) * 32 + 29 + j) * 3072 + c]);
;     }
.LBB0_1176:
	s_or_b64 exec, exec, s[0:1]
	s_waitcnt lgkmcnt(0)
	v_mov_b32_e32 v2, v187
	s_mov_b32 s0, s69
	s_barrier
	v_readfirstlane_b32 s1, v187
	s_cmp_lt_u32 s1, 0x100
	s_cbranch_scc1 .Lprio_gpre_lo
	s_setprio 1
.Lprio_gpre_lo:
	s_ashr_i32 s1, s0, 31
	s_lshl_b64 s[0:1], s[0:1], 9
	v_ashrrev_i32_e32 v3, 31, v2
	v_lshl_add_u64 v[4:5], s[0:1], 0, v[2:3]
	s_mov_b64 s[0:1], 0x6c000
	v_readfirstlane_b32 s8, v2
	v_cmp_gt_u64_e32 vcc, s[0:1], v[4:5]
	s_and_saveexec_b64 s[4:5], vcc
	s_cbranch_execz .LBB0_1192
	v_readlane_b32 s2, v252, 10
	v_readlane_b32 s3, v252, 11
	v_mov_b32_e32 v3, 0x6c000
	s_nop 0
	v_lshl_add_u64 v[6:7], v[4:5], 0, s[2:3]
	v_cmp_lt_u64_e32 vcc, s[0:1], v[6:7]
	v_cmp_gt_u64_e64 s[0:1], s[0:1], v[6:7]
	s_nop 0
	v_cndmask_b32_e32 v3, v3, v6, vcc
	v_cndmask_b32_e64 v8, 0, 1, s[0:1]
	v_cndmask_b32_e32 v0, 0, v7, vcc
	v_sub_co_u32_e32 v3, vcc, v3, v8
	s_nop 1
	v_subbrev_co_u32_e32 v0, vcc, 0, v0, vcc
	v_sub_co_u32_e32 v3, vcc, v3, v6
	v_mov_b32_e32 v6, v1
	s_nop 0
	v_subb_co_u32_e32 v8, vcc, v0, v7, vcc
	v_or_b32_e32 v7, s3, v8
	v_cmp_ne_u64_e32 vcc, 0, v[6:7]
	s_and_saveexec_b64 s[2:3], vcc
	s_xor_b64 s[6:7], exec, s[2:3]
	s_cbranch_execz .LBB0_1179
	v_readlane_b32 s18, v252, 10
	v_readlane_b32 s19, v252, 11
	s_sub_u32 s9, 0, s18
	v_cvt_f32_u32_e32 v0, s18
	v_cvt_f32_u32_e32 v6, s19
	s_subb_u32 s10, 0, s19
	v_fmac_f32_e32 v0, 0x4f800000, v6
	v_rcp_f32_e32 v0, v0
	s_nop 0
	v_mul_f32_e32 v0, 0x5f7ffffc, v0
	v_mul_f32_e32 v6, 0x2f800000, v0
	v_trunc_f32_e32 v6, v6
	v_fmac_f32_e32 v0, 0xcf800000, v6
	v_cvt_u32_f32_e32 v6, v6
	v_cvt_u32_f32_e32 v0, v0
	v_readfirstlane_b32 s11, v6
	v_readfirstlane_b32 s2, v0
	s_mul_i32 s3, s9, s11
	s_mul_hi_u32 s13, s9, s2
	s_mul_i32 s12, s10, s2
	s_add_i32 s3, s13, s3
	s_mul_i32 s14, s9, s2
	s_add_i32 s3, s3, s12
	s_mul_i32 s13, s2, s3
	s_mul_hi_u32 s15, s2, s14
	s_mul_hi_u32 s12, s2, s3
	s_add_u32 s13, s15, s13
	s_addc_u32 s12, 0, s12
	s_mul_hi_u32 s16, s11, s14
	s_mul_i32 s14, s11, s14
	s_add_u32 s13, s13, s14
	s_mul_hi_u32 s15, s11, s3
	s_addc_u32 s12, s12, s16
	s_addc_u32 s13, s15, 0
	s_mul_i32 s3, s11, s3
	s_add_u32 s3, s12, s3
	s_addc_u32 s12, 0, s13
	s_add_u32 s13, s2, s3
	s_cselect_b64 s[2:3], -1, 0
	s_cmp_lg_u64 s[2:3], 0
	s_addc_u32 s11, s11, s12
	s_mul_i32 s2, s9, s11
	s_mul_hi_u32 s3, s9, s13
	s_add_i32 s2, s3, s2
	s_mul_i32 s10, s10, s13
	s_add_i32 s2, s2, s10
	s_mul_i32 s9, s9, s13
	s_mul_hi_u32 s10, s11, s9
	s_mul_i32 s12, s11, s9
	s_mul_i32 s15, s13, s2
	s_mul_hi_u32 s9, s13, s9
	s_mul_hi_u32 s14, s13, s2
	s_add_u32 s9, s9, s15
	s_addc_u32 s14, 0, s14
	s_add_u32 s9, s9, s12
	s_mul_hi_u32 s3, s11, s2
	s_addc_u32 s9, s14, s10
	s_addc_u32 s3, s3, 0
	s_mul_i32 s2, s11, s2
	s_add_u32 s2, s9, s2
	s_addc_u32 s9, 0, s3
	s_add_u32 s10, s13, s2
	s_cselect_b64 s[2:3], -1, 0
	s_cmp_lg_u64 s[2:3], 0
	s_addc_u32 s9, s11, s9
	v_mad_u64_u32 v[6:7], s[2:3], v3, s9, 0
	v_mul_hi_u32 v0, v3, s10
	v_lshl_add_u64 v[6:7], v[0:1], 0, v[6:7]
	v_mad_u64_u32 v[12:13], s[2:3], v8, s10, 0
	v_add_co_u32_e32 v0, vcc, v6, v12
	v_mad_u64_u32 v[10:11], s[2:3], v8, s9, 0
	s_nop 0
	v_addc_co_u32_e32 v0, vcc, v7, v13, vcc
	s_nop 1
	v_addc_co_u32_e32 v11, vcc, 0, v11, vcc
	v_lshl_add_u64 v[6:7], v[0:1], 0, v[10:11]
	v_mul_lo_u32 v0, s19, v6
	v_mul_lo_u32 v9, s18, v7
	v_mad_u64_u32 v[10:11], s[2:3], s18, v6, 0
	v_add3_u32 v0, v11, v9, v0
	v_sub_u32_e32 v9, v8, v0
	v_mov_b32_e32 v11, s19
	v_sub_co_u32_e32 v3, vcc, v3, v10
	v_lshl_add_u64 v[12:13], v[6:7], 0, 1
	s_nop 0
	v_subb_co_u32_e64 v9, s[2:3], v9, v11, vcc
	v_subrev_co_u32_e64 v10, s[2:3], s18, v3
	v_subb_co_u32_e32 v0, vcc, v8, v0, vcc
	s_nop 0
	v_subbrev_co_u32_e64 v9, s[2:3], 0, v9, s[2:3]
	v_cmp_le_u32_e64 s[2:3], s19, v9
	v_cmp_le_u32_e32 vcc, s19, v0
	s_nop 0
	v_cndmask_b32_e64 v11, 0, -1, s[2:3]
	v_cmp_le_u32_e64 s[2:3], s18, v10
	v_cndmask_b32_e64 v8, 0, -1, vcc
	v_cmp_le_u32_e32 vcc, s18, v3
	v_cndmask_b32_e64 v10, 0, -1, s[2:3]
	v_cmp_eq_u32_e64 s[2:3], s19, v9
	v_cndmask_b32_e64 v3, 0, -1, vcc
	v_cmp_eq_u32_e32 vcc, s19, v0
	v_cndmask_b32_e64 v9, v11, v10, s[2:3]
	v_lshl_add_u64 v[10:11], v[6:7], 0, 2
	v_cmp_ne_u32_e64 s[2:3], 0, v9
	v_cndmask_b32_e32 v0, v8, v3, vcc
	v_cmp_ne_u32_e32 vcc, 0, v0
	v_cndmask_b32_e64 v9, v13, v11, s[2:3]
	v_cndmask_b32_e64 v0, v12, v10, s[2:3]
	v_cndmask_b32_e32 v7, v7, v9, vcc
	v_cndmask_b32_e32 v6, v6, v0, vcc

; __device__ __forceinline__ void xcd_barrier(const XcdBarrier& b) {
;     asm volatile("s_waitcnt vmcnt(0)" ::: "memory");
;     __syncthreads();
;     if (threadIdx.x == 0) {
;         unsigned* bar = b.bar;
;         __builtin_amdgcn_s_waitcnt(0);
;         unsigned nloc = b.st[0], nx = b.st[1];
;         if (nloc == 0u) { xcd_barrier_complete(bar, b.x, nloc, nx); b.st[0] = nloc; b.st[1] = nx; }
.LBB0_2321:
	v_readlane_b32 s72, v254, 32
	v_readlane_b32 s76, v254, 37
	v_readlane_b32 s73, v254, 33
	v_readlane_b32 s74, v254, 34
	v_readlane_b32 s75, v254, 35
	v_readlane_b32 s69, v254, 36
	v_readlane_b32 s78, v254, 39
	v_readlane_b32 s79, v254, 40
	v_readlane_b32 s80, v254, 41
	v_readlane_b32 s81, v254, 42
	v_readlane_b32 s77, v254, 38
	v_readlane_b32 s82, v254, 43
	v_readlane_b32 s83, v254, 44
.LBB0_2322:
	s_waitcnt vmcnt(0)
	s_setprio 0
	s_barrier
	s_mov_b64 s[0:1], exec
	v_readlane_b32 s2, v251, 4
	v_readlane_b32 s3, v251, 5
	s_and_b64 s[2:3], s[0:1], s[2:3]
	s_mov_b64 exec, s[2:3]
	s_cbranch_execz .LBB0_2374
	v_readlane_b32 s2, v254, 20
	s_waitcnt vmcnt(0) expcnt(0) lgkmcnt(0)
	s_nop 0
	v_mov_b32_e32 v0, s2
	ds_read_b32 v3, v0
	v_readlane_b32 s2, v254, 21
	s_waitcnt lgkmcnt(0)
	v_cmp_ne_u32_e32 vcc, 0, v3
	v_mov_b32_e32 v0, s2
	ds_read_b32 v2, v0
	s_cbranch_vccnz .LBB0_2338
	s_mov_b32 s8, 1
	s_branch .LBB0_2326
